# code placement: v114 with the in-proj K-loop head moved to the baseline's byte phase (mod 8 = 4) and the out-proj K-loop head to the baseline's mod-64 offset
# speedup vs baseline: 1.0127x; 1.0127x over previous
; template <class Epi, class Sched, bool ALIGN_EPI = false, bool SP2 = false>
; __device__ __forceinline__ void gemm_phase(PG8_LAS unsigned char* lds, const Gemm g, const Sched& S, const Epi& E) {
;     ...
;         const bool has_next = S.next(ui + 1, nxt);
;         const char* nA = has_next ? (const char*)g.A + (size_t)nxt.pm * tstep : cA; const char* nB = has_next ? (const char*)g.Bt + (size_t)nxt.pn * tstep : cB;
;         for (int t = 0; t < nt; t += 2) {
;             const bool last = (t == nt - 2);
;             const char* a1 = cA + (size_t)(t + 1) * kstep;
;             const char* a2 = last ? nA : cA + (size_t)(t + 2) * kstep; const char* b2 = last ? nB : cB + (size_t)(t + 2) * kstep;
;             const char* a3 = a2 + kstep; const char* b3 = b2 + kstep;
;     ...
;         for (int a = 0; a < 2; ++a)
; #pragma unroll
;             for (int b = 0; b < 2; ++b)
; #pragma unroll
;                 for (int m = 0; m < 4; ++m)
; #pragma unroll
;                     for (int n = 0; n < 2; ++n) acc[a][b][m][n] = (f32x4){0.f, 0.f, 0.f, 0.f};
;         cur = nxt; cA = nA; cB = nB; ++ui;
.LBB0_273:
	s_ashr_i32 s13, s12, 31
	s_lshl_b64 s[14:15], s[12:13], 19
	s_add_u32 s14, s46, s14
	s_addc_u32 s15, s47, s15
	s_and_b64 s[16:17], s[0:1], exec
	s_cselect_b32 s5, s15, s21
	s_cselect_b32 s13, s14, s20
	s_ashr_i32 s11, s10, 31
	s_lshl_b64 s[16:17], s[10:11], 19
	s_add_u32 s16, s2, s16
	s_addc_u32 s17, s3, s17
	s_and_b64 s[24:25], s[0:1], exec
	s_cselect_b32 s11, s17, s23
	s_cselect_b32 s35, s16, s22
	s_add_u32 s20, s20, 0x40080
	s_addc_u32 s21, s21, 0
	s_add_u32 s36, s22, 0x100
	v_mov_b32_e32 v0, 0
	s_addc_u32 s37, s23, 0
	s_mov_b32 s38, -2
	v_mov_b32_e32 v1, v0
	v_mov_b32_e32 v2, v0
	v_mov_b32_e32 v3, v0
	v_mov_b32_e32 v4, v0
	v_mov_b32_e32 v5, v0
	v_mov_b32_e32 v6, v0
	v_mov_b32_e32 v7, v0
	v_mov_b32_e32 v16, v0
	v_mov_b32_e32 v17, v0
	v_mov_b32_e32 v18, v0
	v_mov_b32_e32 v19, v0
	v_mov_b32_e32 v20, v0
	v_mov_b32_e32 v21, v0
	v_mov_b32_e32 v22, v0
	v_mov_b32_e32 v23, v0
	v_mov_b32_e32 v32, v0
	v_mov_b32_e32 v33, v0
	v_mov_b32_e32 v34, v0
	v_mov_b32_e32 v35, v0
	v_mov_b32_e32 v36, v0
	v_mov_b32_e32 v37, v0
	v_mov_b32_e32 v38, v0
	v_mov_b32_e32 v39, v0
	v_mov_b32_e32 v48, v0
	v_mov_b32_e32 v49, v0
	v_mov_b32_e32 v50, v0
	v_mov_b32_e32 v51, v0
	v_mov_b32_e32 v52, v0
	v_mov_b32_e32 v53, v0
	v_mov_b32_e32 v54, v0
	v_mov_b32_e32 v55, v0
	v_mov_b32_e32 v8, v0
	v_mov_b32_e32 v9, v0
	v_mov_b32_e32 v10, v0
	v_mov_b32_e32 v11, v0
	v_mov_b32_e32 v12, v0
	v_mov_b32_e32 v13, v0
	v_mov_b32_e32 v14, v0
	v_mov_b32_e32 v15, v0
	v_mov_b32_e32 v24, v0
	v_mov_b32_e32 v25, v0
	v_mov_b32_e32 v26, v0
	v_mov_b32_e32 v27, v0
	v_mov_b32_e32 v28, v0
	v_mov_b32_e32 v29, v0
	v_mov_b32_e32 v30, v0
	v_mov_b32_e32 v31, v0
	v_mov_b32_e32 v40, v0
	v_mov_b32_e32 v41, v0
	v_mov_b32_e32 v42, v0
	v_mov_b32_e32 v43, v0
	v_mov_b32_e32 v44, v0
	v_mov_b32_e32 v45, v0
	v_mov_b32_e32 v46, v0
	v_mov_b32_e32 v47, v0
	v_mov_b32_e32 v56, v0
	v_mov_b32_e32 v57, v0
	v_mov_b32_e32 v58, v0
	v_mov_b32_e32 v59, v0
	v_mov_b32_e32 v60, v0
	v_mov_b32_e32 v61, v0
	v_mov_b32_e32 v62, v0
	v_mov_b32_e32 v63, v0
	v_mov_b32_e32 v64, v0
	v_mov_b32_e32 v65, v0
	v_mov_b32_e32 v66, v0
	v_mov_b32_e32 v67, v0
	v_mov_b32_e32 v68, v0
	v_mov_b32_e32 v69, v0
	v_mov_b32_e32 v70, v0
	v_mov_b32_e32 v71, v0
	v_mov_b32_e32 v80, v0
	v_mov_b32_e32 v81, v0
	v_mov_b32_e32 v82, v0
	v_mov_b32_e32 v83, v0
	v_mov_b32_e32 v84, v0
	v_mov_b32_e32 v85, v0
	v_mov_b32_e32 v86, v0
	v_mov_b32_e32 v87, v0
	v_mov_b32_e32 v96, v0
	v_mov_b32_e32 v97, v0
	v_mov_b32_e32 v98, v0
	v_mov_b32_e32 v99, v0
	v_mov_b32_e32 v100, v0
	v_mov_b32_e32 v101, v0
	v_mov_b32_e32 v102, v0
	v_mov_b32_e32 v103, v0
	v_mov_b32_e32 v112, v0
	v_mov_b32_e32 v113, v0
	v_mov_b32_e32 v114, v0
	v_mov_b32_e32 v115, v0
	v_mov_b32_e32 v116, v0
	v_mov_b32_e32 v117, v0
	v_mov_b32_e32 v118, v0
	v_mov_b32_e32 v119, v0
	v_mov_b32_e32 v72, v0
	v_mov_b32_e32 v73, v0
	v_mov_b32_e32 v74, v0
	v_mov_b32_e32 v75, v0
	v_mov_b32_e32 v76, v0
	v_mov_b32_e32 v77, v0
	v_mov_b32_e32 v78, v0
	v_mov_b32_e32 v79, v0
	v_mov_b32_e32 v88, v0
	v_mov_b32_e32 v89, v0
	v_mov_b32_e32 v90, v0
	v_mov_b32_e32 v91, v0
	v_mov_b32_e32 v92, v0
	v_mov_b32_e32 v93, v0
	v_mov_b32_e32 v94, v0
	v_mov_b32_e32 v95, v0
	v_mov_b32_e32 v104, v0
	v_mov_b32_e32 v105, v0
	v_mov_b32_e32 v106, v0
	v_mov_b32_e32 v107, v0
	v_mov_b32_e32 v108, v0
	v_mov_b32_e32 v109, v0
	v_mov_b32_e32 v110, v0
	v_mov_b32_e32 v111, v0
	v_mov_b32_e32 v120, v0
	v_mov_b32_e32 v121, v0
	v_mov_b32_e32 v122, v0
	v_mov_b32_e32 v123, v0
	v_mov_b32_e32 v124, v0
	v_mov_b32_e32 v125, v0
	v_mov_b32_e32 v126, v0
	v_mov_b32_e32 v127, v0
	s_nop 0

; template <class Epi, class Sched, bool ALIGN_EPI = false, bool SP2 = false>
; __device__ __forceinline__ void gemm_phase(PG8_LAS unsigned char* lds, const Gemm g, const Sched& S, const Epi& E) {
;     ...
;         const bool has_next = S.next(ui + 1, nxt);
;         const char* nA = has_next ? (const char*)g.A + (size_t)nxt.pm * tstep : cA; const char* nB = has_next ? (const char*)g.Bt + (size_t)nxt.pn * tstep : cB;
;         for (int t = 0; t < nt; t += 2) {
;             const bool last = (t == nt - 2);
;             const char* a1 = cA + (size_t)(t + 1) * kstep;
;             const char* a2 = last ? nA : cA + (size_t)(t + 2) * kstep; const char* b2 = last ? nB : cB + (size_t)(t + 2) * kstep;
;             const char* a3 = a2 + kstep; const char* b3 = b2 + kstep;
;     ...
;         for (int a = 0; a < 2; ++a)
; #pragma unroll
;             for (int b = 0; b < 2; ++b)
; #pragma unroll
;                 for (int m = 0; m < 4; ++m)
; #pragma unroll
;                     for (int n = 0; n < 2; ++n) acc[a][b][m][n] = (f32x4){0.f, 0.f, 0.f, 0.f};
;         cur = nxt; cA = nA; cB = nB; ++ui;
.LBB0_612:
	s_ashr_i32 s27, s26, 31
	s_lshl_b64 s[28:29], s[26:27], 19
	s_add_u32 s28, s46, s28
	s_addc_u32 s29, s47, s29
	s_and_b64 s[30:31], s[0:1], exec
	s_cselect_b32 s27, s29, s35
	s_cselect_b32 s63, s28, s34
	s_ashr_i32 s25, s24, 31
	s_lshl_b64 s[30:31], s[24:25], 19
	s_add_u32 s30, s2, s30
	s_addc_u32 s31, s3, s31
	s_and_b64 s[38:39], s[0:1], exec
	s_cselect_b32 s25, s31, s37
	s_cselect_b32 s64, s30, s36
	s_add_u32 s34, s34, 0x40080
	s_addc_u32 s35, s35, 0
	s_add_u32 s65, s36, 0x100
	v_mov_b32_e32 v0, 0
	s_addc_u32 s66, s37, 0
	s_mov_b32 s67, -2
	v_mov_b32_e32 v1, v0
	v_mov_b32_e32 v2, v0
	v_mov_b32_e32 v3, v0
	v_mov_b32_e32 v4, v0
	v_mov_b32_e32 v5, v0
	v_mov_b32_e32 v6, v0
	v_mov_b32_e32 v7, v0
	v_mov_b32_e32 v16, v0
	v_mov_b32_e32 v17, v0
	v_mov_b32_e32 v18, v0
	v_mov_b32_e32 v19, v0
	v_mov_b32_e32 v20, v0
	v_mov_b32_e32 v21, v0
	v_mov_b32_e32 v22, v0
	v_mov_b32_e32 v23, v0
	v_mov_b32_e32 v32, v0
	v_mov_b32_e32 v33, v0
	v_mov_b32_e32 v34, v0
	v_mov_b32_e32 v35, v0
	v_mov_b32_e32 v36, v0
	v_mov_b32_e32 v37, v0
	v_mov_b32_e32 v38, v0
	v_mov_b32_e32 v39, v0
	v_mov_b32_e32 v48, v0
	v_mov_b32_e32 v49, v0
	v_mov_b32_e32 v50, v0
	v_mov_b32_e32 v51, v0
	v_mov_b32_e32 v52, v0
	v_mov_b32_e32 v53, v0
	v_mov_b32_e32 v54, v0
	v_mov_b32_e32 v55, v0
	v_mov_b32_e32 v8, v0
	v_mov_b32_e32 v9, v0
	v_mov_b32_e32 v10, v0
	v_mov_b32_e32 v11, v0
	v_mov_b32_e32 v12, v0
	v_mov_b32_e32 v13, v0
	v_mov_b32_e32 v14, v0
	v_mov_b32_e32 v15, v0
	v_mov_b32_e32 v24, v0
	v_mov_b32_e32 v25, v0
	v_mov_b32_e32 v26, v0
	v_mov_b32_e32 v27, v0
	v_mov_b32_e32 v28, v0
	v_mov_b32_e32 v29, v0
	v_mov_b32_e32 v30, v0
	v_mov_b32_e32 v31, v0
	v_mov_b32_e32 v40, v0
	v_mov_b32_e32 v41, v0
	v_mov_b32_e32 v42, v0
	v_mov_b32_e32 v43, v0
	v_mov_b32_e32 v44, v0
	v_mov_b32_e32 v45, v0
	v_mov_b32_e32 v46, v0
	v_mov_b32_e32 v47, v0
	v_mov_b32_e32 v56, v0
	v_mov_b32_e32 v57, v0
	v_mov_b32_e32 v58, v0
	v_mov_b32_e32 v59, v0
	v_mov_b32_e32 v60, v0
	v_mov_b32_e32 v61, v0
	v_mov_b32_e32 v62, v0
	v_mov_b32_e32 v63, v0
	v_mov_b32_e32 v64, v0
	v_mov_b32_e32 v65, v0
	v_mov_b32_e32 v66, v0
	v_mov_b32_e32 v67, v0
	v_mov_b32_e32 v76, v0
	v_mov_b32_e32 v77, v0
	v_mov_b32_e32 v78, v0
	v_mov_b32_e32 v79, v0
	v_mov_b32_e32 v96, v0
	v_mov_b32_e32 v97, v0
	v_mov_b32_e32 v98, v0
	v_mov_b32_e32 v99, v0
	v_mov_b32_e32 v100, v0
	v_mov_b32_e32 v101, v0
	v_mov_b32_e32 v102, v0
	v_mov_b32_e32 v103, v0
	v_mov_b32_e32 v112, v0
	v_mov_b32_e32 v113, v0
	v_mov_b32_e32 v114, v0
	v_mov_b32_e32 v115, v0
	v_mov_b32_e32 v116, v0
	v_mov_b32_e32 v117, v0
	v_mov_b32_e32 v118, v0
	v_mov_b32_e32 v119, v0
	v_mov_b32_e32 v128, v0
	v_mov_b32_e32 v129, v0
	v_mov_b32_e32 v130, v0
	v_mov_b32_e32 v131, v0
	v_mov_b32_e32 v132, v0
	v_mov_b32_e32 v133, v0
	v_mov_b32_e32 v134, v0
	v_mov_b32_e32 v135, v0
	v_mov_b32_e32 v88, v0
	v_mov_b32_e32 v89, v0
	v_mov_b32_e32 v90, v0
	v_mov_b32_e32 v91, v0
	v_mov_b32_e32 v92, v0
	v_mov_b32_e32 v93, v0
	v_mov_b32_e32 v94, v0
	v_mov_b32_e32 v95, v0
	v_mov_b32_e32 v104, v0
	v_mov_b32_e32 v105, v0
	v_mov_b32_e32 v106, v0
	v_mov_b32_e32 v107, v0
	v_mov_b32_e32 v108, v0
	v_mov_b32_e32 v109, v0
	v_mov_b32_e32 v110, v0
	v_mov_b32_e32 v111, v0
	v_mov_b32_e32 v120, v0
	v_mov_b32_e32 v121, v0
	v_mov_b32_e32 v122, v0
	v_mov_b32_e32 v123, v0
	v_mov_b32_e32 v124, v0
	v_mov_b32_e32 v125, v0
	v_mov_b32_e32 v126, v0
	v_mov_b32_e32 v127, v0
	v_mov_b32_e32 v136, v0
	v_mov_b32_e32 v137, v0
	v_mov_b32_e32 v138, v0
	v_mov_b32_e32 v139, v0
	v_mov_b32_e32 v140, v0
	v_mov_b32_e32 v141, v0
	v_mov_b32_e32 v142, v0
	v_mov_b32_e32 v143, v0
	s_nop 0
